# top-k mask ballots software-pipelined over 4 SGPR pairs (drops s_nop 4 per chunk); FA QK vmcnt ladder removed
# baseline (speedup 1.0000x reference)
; #define TK_WL2(dlo, dhi, vlo, vhi, ln) asm volatile("s_nop 4\n\tv_writelane_b32 %0, %2, %4\n\tv_writelane_b32 %1, %3, %4" : "+v"(dlo), "+v"(dhi) : "s"(vlo), "s"(vhi), "n"(ln))
; template <int NCH>
; __device__ __forceinline__ void dsa_topk_query(unsigned char* ws, const float* srow  , LAS unsigned* hist  , int t, int lane_in) {
;     ...
;     if (ge) {
;         int a_lo = 0, a_hi = 0, b_lo = 0, b_hi = 0;
;     ...
; #pragma unroll
;         for (int c = 0; c < NCH; ++c) { const u64 sm = __ballot(u[c] >= T); const int slo = (int)(unsigned)sm, shi = (int)(unsigned)(sm >> 32);
;             if (c < 64) TK_WL2(a_lo, a_hi, slo, shi, c & 63); else TK_WL2(b_lo, b_hi, slo, shi, c & 63); }
;     ...
;         bm[lane] = ((u64)(unsigned)a_hi << 32) | (unsigned)a_lo; bm[64 + lane] = ((u64)(unsigned)b_hi << 32) | (unsigned)b_lo;
;         return;
.LBB0_3250:
	s_and_b64 vcc, exec, s[0:1]
	s_cbranch_vccz .LBB0_3252
	v_cmp_ge_u32_e32 vcc, v128, v126
	v_mov_b32_e32 v142, 0
	v_mov_b32_e32 v143, 0
	v_cmp_ge_u32_e64 s[6:7], v1, v126
	v_cmp_ge_u32_e64 s[8:9], v140, v126
	s_nop 1
	v_writelane_b32 v142, vcc_lo, 0
	v_writelane_b32 v143, vcc_hi, 0
	v_cmp_ge_u32_e64 s[40:41], v129, v126
	v_writelane_b32 v142, s6, 1
	v_writelane_b32 v143, s7, 1
	v_cmp_ge_u32_e32 vcc, v130, v126
	v_writelane_b32 v142, s8, 2
	v_writelane_b32 v143, s9, 2
	v_cmp_ge_u32_e64 s[6:7], v125, v126
	v_writelane_b32 v142, s40, 3
	v_writelane_b32 v143, s41, 3
	v_cmp_ge_u32_e64 s[8:9], v124, v126
	v_writelane_b32 v142, vcc_lo, 4
	v_writelane_b32 v143, vcc_hi, 4
	v_cmp_ge_u32_e64 s[40:41], v127, v126
	v_writelane_b32 v142, s6, 5
	v_writelane_b32 v143, s7, 5
	v_cmp_ge_u32_e32 vcc, v2, v126
	v_writelane_b32 v142, s8, 6
	v_writelane_b32 v143, s9, 6
	v_cmp_ge_u32_e64 s[6:7], v121, v126
	v_writelane_b32 v142, s40, 7
	v_writelane_b32 v143, s41, 7
	v_cmp_ge_u32_e64 s[8:9], v120, v126
	v_writelane_b32 v142, vcc_lo, 8
	v_writelane_b32 v143, vcc_hi, 8
	v_cmp_ge_u32_e64 s[40:41], v123, v126
	v_writelane_b32 v142, s6, 9
	v_writelane_b32 v143, s7, 9
	v_cmp_ge_u32_e32 vcc, v116, v126
	v_writelane_b32 v142, s8, 10
	v_writelane_b32 v143, s9, 10
	v_cmp_ge_u32_e64 s[6:7], v117, v126
	v_writelane_b32 v142, s40, 11
	v_writelane_b32 v143, s41, 11
	v_cmp_ge_u32_e64 s[8:9], v118, v126
	v_writelane_b32 v142, vcc_lo, 12
	v_writelane_b32 v143, vcc_hi, 12
	v_cmp_ge_u32_e64 s[40:41], v119, v126
	v_writelane_b32 v142, s6, 13
	v_writelane_b32 v143, s7, 13
	v_cmp_ge_u32_e32 vcc, v112, v126
	v_writelane_b32 v142, s8, 14
	v_writelane_b32 v143, s9, 14
	v_cmp_ge_u32_e64 s[6:7], v113, v126
	v_writelane_b32 v142, s40, 15
	v_writelane_b32 v143, s41, 15
	v_cmp_ge_u32_e64 s[8:9], v114, v126
	v_writelane_b32 v142, vcc_lo, 16
	v_writelane_b32 v143, vcc_hi, 16
	v_cmp_ge_u32_e64 s[40:41], v115, v126
	v_writelane_b32 v142, s6, 17
	v_writelane_b32 v143, s7, 17
	v_cmp_ge_u32_e32 vcc, v108, v126
	v_writelane_b32 v142, s8, 18
	v_writelane_b32 v143, s9, 18
	v_cmp_ge_u32_e64 s[6:7], v109, v126
	v_writelane_b32 v142, s40, 19
	v_writelane_b32 v143, s41, 19
	v_cmp_ge_u32_e64 s[8:9], v110, v126
	v_writelane_b32 v142, vcc_lo, 20
	v_writelane_b32 v143, vcc_hi, 20
	v_cmp_ge_u32_e64 s[40:41], v111, v126
	v_writelane_b32 v142, s6, 21
	v_writelane_b32 v143, s7, 21
	v_cmp_ge_u32_e32 vcc, v104, v126
	v_writelane_b32 v142, s8, 22
	v_writelane_b32 v143, s9, 22
	v_cmp_ge_u32_e64 s[6:7], v105, v126
	v_writelane_b32 v142, s40, 23
	v_writelane_b32 v143, s41, 23
	v_cmp_ge_u32_e64 s[8:9], v106, v126
	v_writelane_b32 v142, vcc_lo, 24
	v_writelane_b32 v143, vcc_hi, 24
	v_cmp_ge_u32_e64 s[40:41], v107, v126
	v_writelane_b32 v142, s6, 25
	v_writelane_b32 v143, s7, 25
	v_cmp_ge_u32_e32 vcc, v100, v126
	v_writelane_b32 v142, s8, 26
	v_writelane_b32 v143, s9, 26
	v_cmp_ge_u32_e64 s[6:7], v101, v126
	v_writelane_b32 v142, s40, 27
	v_writelane_b32 v143, s41, 27
	v_cmp_ge_u32_e64 s[8:9], v102, v126
	v_writelane_b32 v142, vcc_lo, 28
	v_writelane_b32 v143, vcc_hi, 28
	v_cmp_ge_u32_e64 s[40:41], v103, v126
	v_writelane_b32 v142, s6, 29
	v_writelane_b32 v143, s7, 29
	v_cmp_ge_u32_e32 vcc, v96, v126
	v_writelane_b32 v142, s8, 30
	v_writelane_b32 v143, s9, 30
	v_cmp_ge_u32_e64 s[6:7], v97, v126
	v_writelane_b32 v142, s40, 31
	v_writelane_b32 v143, s41, 31
	v_cmp_ge_u32_e64 s[8:9], v98, v126
	v_writelane_b32 v142, vcc_lo, 32
	v_writelane_b32 v143, vcc_hi, 32
	v_cmp_ge_u32_e64 s[40:41], v99, v126
	v_writelane_b32 v142, s6, 33
	v_writelane_b32 v143, s7, 33
	v_cmp_ge_u32_e32 vcc, v92, v126
	v_writelane_b32 v142, s8, 34
	v_writelane_b32 v143, s9, 34
	v_cmp_ge_u32_e64 s[6:7], v93, v126
	v_writelane_b32 v142, s40, 35
	v_writelane_b32 v143, s41, 35
	v_cmp_ge_u32_e64 s[8:9], v94, v126
	v_writelane_b32 v142, vcc_lo, 36
	v_writelane_b32 v143, vcc_hi, 36
	v_cmp_ge_u32_e64 s[40:41], v95, v126
	v_writelane_b32 v142, s6, 37
	v_writelane_b32 v143, s7, 37
	v_cmp_ge_u32_e32 vcc, v88, v126
	v_writelane_b32 v142, s8, 38
	v_writelane_b32 v143, s9, 38
	v_cmp_ge_u32_e64 s[6:7], v89, v126
	v_writelane_b32 v142, s40, 39
	v_writelane_b32 v143, s41, 39
	v_cmp_ge_u32_e64 s[8:9], v90, v126
	v_writelane_b32 v142, vcc_lo, 40
	v_writelane_b32 v143, vcc_hi, 40
	v_cmp_ge_u32_e64 s[40:41], v91, v126
	v_writelane_b32 v142, s6, 41
	v_writelane_b32 v143, s7, 41
	v_cmp_ge_u32_e32 vcc, v84, v126
	v_writelane_b32 v142, s8, 42
	v_writelane_b32 v143, s9, 42
	v_cmp_ge_u32_e64 s[6:7], v85, v126
	v_writelane_b32 v142, s40, 43
	v_writelane_b32 v143, s41, 43
	v_cmp_ge_u32_e64 s[8:9], v86, v126
	v_writelane_b32 v142, vcc_lo, 44
	v_writelane_b32 v143, vcc_hi, 44
	v_cmp_ge_u32_e64 s[40:41], v87, v126
	v_writelane_b32 v142, s6, 45
	v_writelane_b32 v143, s7, 45
	v_cmp_ge_u32_e32 vcc, v80, v126
	v_writelane_b32 v142, s8, 46
	v_writelane_b32 v143, s9, 46
	v_cmp_ge_u32_e64 s[6:7], v81, v126
	v_writelane_b32 v142, s40, 47
	v_writelane_b32 v143, s41, 47
	v_cmp_ge_u32_e64 s[8:9], v82, v126
	v_writelane_b32 v142, vcc_lo, 48
	v_writelane_b32 v143, vcc_hi, 48
	v_cmp_ge_u32_e64 s[40:41], v83, v126
	v_writelane_b32 v142, s6, 49
	v_writelane_b32 v143, s7, 49
	v_cmp_ge_u32_e32 vcc, v76, v126
	v_writelane_b32 v142, s8, 50
	v_writelane_b32 v143, s9, 50
	v_cmp_ge_u32_e64 s[6:7], v77, v126
	v_writelane_b32 v142, s40, 51
	v_writelane_b32 v143, s41, 51
	v_cmp_ge_u32_e64 s[8:9], v78, v126
	v_writelane_b32 v142, vcc_lo, 52
	v_writelane_b32 v143, vcc_hi, 52
	v_cmp_ge_u32_e64 s[40:41], v79, v126
	v_writelane_b32 v142, s6, 53
	v_writelane_b32 v143, s7, 53
	v_cmp_ge_u32_e32 vcc, v72, v126
	v_writelane_b32 v142, s8, 54
	v_writelane_b32 v143, s9, 54
	v_cmp_ge_u32_e64 s[6:7], v73, v126
; #define TK_WL2(dlo, dhi, vlo, vhi, ln) asm volatile("s_nop 4\n\tv_writelane_b32 %0, %2, %4\n\tv_writelane_b32 %1, %3, %4" : "+v"(dlo), "+v"(dhi) : "s"(vlo), "s"(vhi), "n"(ln))
; template <int NCH>
; __device__ __forceinline__ void dsa_topk_query(unsigned char* ws, const float* srow  , LAS unsigned* hist  , int t, int lane_in) {
;     ...
;     if (ge) {
;         int a_lo = 0, a_hi = 0, b_lo = 0, b_hi = 0;
;     ...
; #pragma unroll
;         for (int c = 0; c < NCH; ++c) { const u64 sm = __ballot(u[c] >= T); const int slo = (int)(unsigned)sm, shi = (int)(unsigned)(sm >> 32);
;             if (c < 64) TK_WL2(a_lo, a_hi, slo, shi, c & 63); else TK_WL2(b_lo, b_hi, slo, shi, c & 63); }
;     ...
;         bm[lane] = ((u64)(unsigned)a_hi << 32) | (unsigned)a_lo; bm[64 + lane] = ((u64)(unsigned)b_hi << 32) | (unsigned)b_lo;
;         return;
	v_writelane_b32 v142, s40, 55
	v_writelane_b32 v143, s41, 55
	v_cmp_ge_u32_e64 s[8:9], v74, v126
	v_writelane_b32 v142, vcc_lo, 56
	v_writelane_b32 v143, vcc_hi, 56
	v_cmp_ge_u32_e64 s[40:41], v75, v126
	v_writelane_b32 v142, s6, 57
	v_writelane_b32 v143, s7, 57
	v_cmp_ge_u32_e32 vcc, v68, v126
	v_writelane_b32 v142, s8, 58
	v_writelane_b32 v143, s9, 58
	v_cmp_ge_u32_e64 s[6:7], v69, v126
	v_writelane_b32 v142, s40, 59
	v_writelane_b32 v143, s41, 59
	v_cmp_ge_u32_e64 s[8:9], v70, v126
	v_writelane_b32 v142, vcc_lo, 60
	v_writelane_b32 v143, vcc_hi, 60
	v_cmp_ge_u32_e64 s[40:41], v71, v126
	v_writelane_b32 v142, s6, 61
	v_writelane_b32 v143, s7, 61
	v_cmp_ge_u32_e32 vcc, v64, v126
	v_mov_b32_e32 v68, 0
	v_mov_b32_e32 v69, 0
	v_writelane_b32 v142, s8, 62
	v_writelane_b32 v143, s9, 62
	v_cmp_ge_u32_e64 s[6:7], v65, v126
	v_writelane_b32 v142, s40, 63
	v_writelane_b32 v143, s41, 63
	v_cmp_ge_u32_e64 s[8:9], v66, v126
	v_writelane_b32 v68, vcc_lo, 0
	v_writelane_b32 v69, vcc_hi, 0
	v_cmp_ge_u32_e64 s[40:41], v67, v126
	v_writelane_b32 v68, s6, 1
	v_writelane_b32 v69, s7, 1
	v_cmp_ge_u32_e32 vcc, v60, v126
	v_writelane_b32 v68, s8, 2
	v_writelane_b32 v69, s9, 2
	v_cmp_ge_u32_e64 s[6:7], v61, v126
	v_writelane_b32 v68, s40, 3
	v_writelane_b32 v69, s41, 3
	v_cmp_ge_u32_e64 s[8:9], v62, v126
	v_writelane_b32 v68, vcc_lo, 4
	v_writelane_b32 v69, vcc_hi, 4
	v_cmp_ge_u32_e64 s[40:41], v63, v126
	v_writelane_b32 v68, s6, 5
	v_writelane_b32 v69, s7, 5
	v_cmp_ge_u32_e32 vcc, v56, v126
	v_writelane_b32 v68, s8, 6
	v_writelane_b32 v69, s9, 6
	v_cmp_ge_u32_e64 s[6:7], v57, v126
	v_writelane_b32 v68, s40, 7
	v_writelane_b32 v69, s41, 7
	v_cmp_ge_u32_e64 s[8:9], v58, v126
	v_writelane_b32 v68, vcc_lo, 8
	v_writelane_b32 v69, vcc_hi, 8
	v_cmp_ge_u32_e64 s[40:41], v59, v126
	v_writelane_b32 v68, s6, 9
	v_writelane_b32 v69, s7, 9
	v_cmp_ge_u32_e32 vcc, v52, v126
	v_writelane_b32 v68, s8, 10
	v_writelane_b32 v69, s9, 10
	v_cmp_ge_u32_e64 s[6:7], v53, v126
	v_writelane_b32 v68, s40, 11
	v_writelane_b32 v69, s41, 11
	v_cmp_ge_u32_e64 s[8:9], v54, v126
	v_writelane_b32 v68, vcc_lo, 12
	v_writelane_b32 v69, vcc_hi, 12
	v_cmp_ge_u32_e64 s[40:41], v55, v126
	v_writelane_b32 v68, s6, 13
	v_writelane_b32 v69, s7, 13
	v_cmp_ge_u32_e32 vcc, v48, v126
	v_writelane_b32 v68, s8, 14
	v_writelane_b32 v69, s9, 14
	v_cmp_ge_u32_e64 s[6:7], v49, v126
	v_writelane_b32 v68, s40, 15
	v_writelane_b32 v69, s41, 15
	v_cmp_ge_u32_e64 s[8:9], v50, v126
	v_writelane_b32 v68, vcc_lo, 16
	v_writelane_b32 v69, vcc_hi, 16
	v_cmp_ge_u32_e64 s[40:41], v51, v126
	v_writelane_b32 v68, s6, 17
	v_writelane_b32 v69, s7, 17
	v_cmp_ge_u32_e32 vcc, v44, v126
	v_writelane_b32 v68, s8, 18
	v_writelane_b32 v69, s9, 18
	v_cmp_ge_u32_e64 s[6:7], v45, v126
	v_writelane_b32 v68, s40, 19
	v_writelane_b32 v69, s41, 19
	v_cmp_ge_u32_e64 s[8:9], v46, v126
	v_writelane_b32 v68, vcc_lo, 20
	v_writelane_b32 v69, vcc_hi, 20
	v_cmp_ge_u32_e64 s[40:41], v47, v126
	v_writelane_b32 v68, s6, 21
	v_writelane_b32 v69, s7, 21
	v_cmp_ge_u32_e32 vcc, v40, v126
	v_writelane_b32 v68, s8, 22
	v_writelane_b32 v69, s9, 22
	v_cmp_ge_u32_e64 s[6:7], v41, v126
	v_writelane_b32 v68, s40, 23
	v_writelane_b32 v69, s41, 23
	v_cmp_ge_u32_e64 s[8:9], v42, v126
	v_writelane_b32 v68, vcc_lo, 24
	v_writelane_b32 v69, vcc_hi, 24
	v_cmp_ge_u32_e64 s[40:41], v43, v126
	v_writelane_b32 v68, s6, 25
	v_writelane_b32 v69, s7, 25
	v_cmp_ge_u32_e32 vcc, v36, v126
	v_writelane_b32 v68, s8, 26
	v_writelane_b32 v69, s9, 26
	v_cmp_ge_u32_e64 s[6:7], v37, v126
	v_writelane_b32 v68, s40, 27
	v_writelane_b32 v69, s41, 27
; #define TK_WL2(dlo, dhi, vlo, vhi, ln) asm volatile("s_nop 4\n\tv_writelane_b32 %0, %2, %4\n\tv_writelane_b32 %1, %3, %4" : "+v"(dlo), "+v"(dhi) : "s"(vlo), "s"(vhi), "n"(ln))
; template <int NCH>
; __device__ __forceinline__ void dsa_topk_query(unsigned char* ws, const float* srow  , LAS unsigned* hist  , int t, int lane_in) {
;     ...
;     if (ge) {
;         int a_lo = 0, a_hi = 0, b_lo = 0, b_hi = 0;
;     ...
; #pragma unroll
;         for (int c = 0; c < NCH; ++c) { const u64 sm = __ballot(u[c] >= T); const int slo = (int)(unsigned)sm, shi = (int)(unsigned)(sm >> 32);
;             if (c < 64) TK_WL2(a_lo, a_hi, slo, shi, c & 63); else TK_WL2(b_lo, b_hi, slo, shi, c & 63); }
;     ...
;         bm[lane] = ((u64)(unsigned)a_hi << 32) | (unsigned)a_lo; bm[64 + lane] = ((u64)(unsigned)b_hi << 32) | (unsigned)b_lo;
;         return;
	v_cmp_ge_u32_e64 s[8:9], v38, v126
	v_writelane_b32 v68, vcc_lo, 28
	v_writelane_b32 v69, vcc_hi, 28
	v_cmp_ge_u32_e64 s[40:41], v39, v126
	v_writelane_b32 v68, s6, 29
	v_writelane_b32 v69, s7, 29
	v_cmp_ge_u32_e32 vcc, v28, v126
	v_writelane_b32 v68, s8, 30
	v_writelane_b32 v69, s9, 30
	v_cmp_ge_u32_e64 s[6:7], v29, v126
	v_writelane_b32 v68, s40, 31
	v_writelane_b32 v69, s41, 31
	v_cmp_ge_u32_e64 s[8:9], v30, v126
	v_writelane_b32 v68, vcc_lo, 32
	v_writelane_b32 v69, vcc_hi, 32
	v_cmp_ge_u32_e64 s[40:41], v31, v126
	v_writelane_b32 v68, s6, 33
	v_writelane_b32 v69, s7, 33
	v_cmp_ge_u32_e32 vcc, v24, v126
	v_writelane_b32 v68, s8, 34
	v_writelane_b32 v69, s9, 34
	v_cmp_ge_u32_e64 s[6:7], v25, v126
	v_writelane_b32 v68, s40, 35
	v_writelane_b32 v69, s41, 35
	v_cmp_ge_u32_e64 s[8:9], v26, v126
	v_writelane_b32 v68, vcc_lo, 36
	v_writelane_b32 v69, vcc_hi, 36
	v_cmp_ge_u32_e64 s[40:41], v27, v126
	v_writelane_b32 v68, s6, 37
	v_writelane_b32 v69, s7, 37
	v_cmp_ge_u32_e32 vcc, v16, v126
	v_writelane_b32 v68, s8, 38
	v_writelane_b32 v69, s9, 38
	v_cmp_ge_u32_e64 s[6:7], v17, v126
	v_writelane_b32 v68, s40, 39
	v_writelane_b32 v69, s41, 39
	v_cmp_ge_u32_e64 s[8:9], v18, v126
	v_writelane_b32 v68, vcc_lo, 40
	v_writelane_b32 v69, vcc_hi, 40
	v_cmp_ge_u32_e64 s[40:41], v19, v126
	v_writelane_b32 v68, s6, 41
	v_writelane_b32 v69, s7, 41
	v_cmp_ge_u32_e32 vcc, v8, v126
	v_writelane_b32 v68, s8, 42
	v_writelane_b32 v69, s9, 42
	v_cmp_ge_u32_e64 s[6:7], v9, v126
	v_writelane_b32 v68, s40, 43
	v_writelane_b32 v69, s41, 43
	v_cmp_ge_u32_e64 s[8:9], v10, v126
	v_writelane_b32 v68, vcc_lo, 44
	v_writelane_b32 v69, vcc_hi, 44
	v_cmp_ge_u32_e64 s[40:41], v11, v126
	v_writelane_b32 v68, s6, 45
	v_writelane_b32 v69, s7, 45
	v_cmp_ge_u32_e32 vcc, v32, v126
	v_writelane_b32 v68, s8, 46
	v_writelane_b32 v69, s9, 46
	v_cmp_ge_u32_e64 s[6:7], v33, v126
	v_writelane_b32 v68, s40, 47
	v_writelane_b32 v69, s41, 47
	v_cmp_ge_u32_e64 s[8:9], v34, v126
	v_writelane_b32 v68, vcc_lo, 48
	v_writelane_b32 v69, vcc_hi, 48
	v_cmp_ge_u32_e64 s[40:41], v35, v126
	v_writelane_b32 v68, s6, 49
	v_writelane_b32 v69, s7, 49
	v_cmp_ge_u32_e32 vcc, v20, v126
	v_writelane_b32 v68, s8, 50
	v_writelane_b32 v69, s9, 50
	v_cmp_ge_u32_e64 s[6:7], v21, v126
	v_writelane_b32 v68, s40, 51
	v_writelane_b32 v69, s41, 51
	v_cmp_ge_u32_e64 s[8:9], v22, v126
	v_writelane_b32 v68, vcc_lo, 52
	v_writelane_b32 v69, vcc_hi, 52
	v_cmp_ge_u32_e64 s[40:41], v23, v126
	v_writelane_b32 v68, s6, 53
	v_writelane_b32 v69, s7, 53
	v_cmp_ge_u32_e32 vcc, v12, v126
	v_writelane_b32 v68, s8, 54
	v_writelane_b32 v69, s9, 54
	v_cmp_ge_u32_e64 s[6:7], v13, v126
	v_writelane_b32 v68, s40, 55
	v_writelane_b32 v69, s41, 55
	v_cmp_ge_u32_e64 s[8:9], v14, v126
	v_writelane_b32 v68, vcc_lo, 56
	v_writelane_b32 v69, vcc_hi, 56
	v_cmp_ge_u32_e64 s[40:41], v15, v126
	v_writelane_b32 v68, s6, 57
	v_writelane_b32 v69, s7, 57
	v_cmp_ge_u32_e32 vcc, v4, v126
	v_writelane_b32 v68, s8, 58
	v_writelane_b32 v69, s9, 58
	v_cmp_ge_u32_e64 s[6:7], v5, v126
	v_writelane_b32 v68, s40, 59
	v_writelane_b32 v69, s41, 59
	v_cmp_ge_u32_e64 s[8:9], v6, v126
	v_writelane_b32 v68, vcc_lo, 60
	v_writelane_b32 v69, vcc_hi, 60
	v_cmp_ge_u32_e64 s[40:41], v7, v126
	v_lshl_add_u64 v[4:5], v[138:139], 3, s[60:61]
	v_writelane_b32 v68, s6, 61
	v_writelane_b32 v69, s7, 61
	v_writelane_b32 v68, s8, 62
	v_writelane_b32 v69, s9, 62
	v_writelane_b32 v68, s40, 63
	v_writelane_b32 v69, s41, 63
	global_store_dwordx2 v[4:5], v[142:143], off
	global_store_dwordx2 v[4:5], v[68:69], off offset:512

; #define TK_WL2(dlo, dhi, vlo, vhi, ln) asm volatile("s_nop 4\n\tv_writelane_b32 %0, %2, %4\n\tv_writelane_b32 %1, %3, %4" : "+v"(dlo), "+v"(dhi) : "s"(vlo), "s"(vhi), "n"(ln))
; template <int NCH>
; __device__ __forceinline__ void dsa_topk_query(unsigned char* ws, const float* srow  , LAS unsigned* hist  , int t, int lane_in) {
;     ...
;     if (ge) {
;         int a_lo = 0, a_hi = 0, b_lo = 0, b_hi = 0;
;     ...
; #pragma unroll
;         for (int c = 0; c < NCH; ++c) { const u64 sm = __ballot(u[c] >= T); const int slo = (int)(unsigned)sm, shi = (int)(unsigned)(sm >> 32);
;             if (c < 64) TK_WL2(a_lo, a_hi, slo, shi, c & 63); else TK_WL2(b_lo, b_hi, slo, shi, c & 63); }
;     ...
;         bm[lane] = ((u64)(unsigned)a_hi << 32) | (unsigned)a_lo; bm[64 + lane] = ((u64)(unsigned)b_hi << 32) | (unsigned)b_lo;
;         return;
.LBB0_3982:
	s_and_b64 vcc, exec, s[0:1]
	s_cbranch_vccz .LBB0_3985
	v_cmp_ge_u32_e32 vcc, v106, v74
	v_mov_b32_e32 v38, 0
	v_mov_b32_e32 v39, 0
	v_cmp_ge_u32_e64 s[6:7], v107, v74
	v_cmp_ge_u32_e64 s[8:9], v104, v74
	s_nop 1
	v_writelane_b32 v38, vcc_lo, 0
	v_writelane_b32 v39, vcc_hi, 0
	v_cmp_ge_u32_e64 s[40:41], v105, v74
	v_writelane_b32 v38, s6, 1
	v_writelane_b32 v39, s7, 1
	v_cmp_ge_u32_e32 vcc, v102, v74
	v_writelane_b32 v38, s8, 2
	v_writelane_b32 v39, s9, 2
	v_cmp_ge_u32_e64 s[6:7], v101, v74
	v_writelane_b32 v38, s40, 3
	v_writelane_b32 v39, s41, 3
	v_cmp_ge_u32_e64 s[8:9], v100, v74
	v_writelane_b32 v38, vcc_lo, 4
	v_writelane_b32 v39, vcc_hi, 4
	v_cmp_ge_u32_e64 s[40:41], v103, v74
	v_writelane_b32 v38, s6, 5
	v_writelane_b32 v39, s7, 5
	v_cmp_ge_u32_e32 vcc, v98, v74
	v_writelane_b32 v38, s8, 6
	v_writelane_b32 v39, s9, 6
	v_cmp_ge_u32_e64 s[6:7], v99, v74
	v_writelane_b32 v38, s40, 7
	v_writelane_b32 v39, s41, 7
	v_cmp_ge_u32_e64 s[8:9], v96, v74
	v_writelane_b32 v38, vcc_lo, 8
	v_writelane_b32 v39, vcc_hi, 8
	v_cmp_ge_u32_e64 s[40:41], v97, v74
	v_writelane_b32 v38, s6, 9
	v_writelane_b32 v39, s7, 9
	v_cmp_ge_u32_e32 vcc, v94, v74
	v_writelane_b32 v38, s8, 10
	v_writelane_b32 v39, s9, 10
	v_cmp_ge_u32_e64 s[6:7], v95, v74
	v_writelane_b32 v38, s40, 11
	v_writelane_b32 v39, s41, 11
	v_cmp_ge_u32_e64 s[8:9], v92, v74
	v_writelane_b32 v38, vcc_lo, 12
	v_writelane_b32 v39, vcc_hi, 12
	v_cmp_ge_u32_e64 s[40:41], v93, v74
	v_writelane_b32 v38, s6, 13
	v_writelane_b32 v39, s7, 13
	v_cmp_ge_u32_e32 vcc, v90, v74
	v_writelane_b32 v38, s8, 14
	v_writelane_b32 v39, s9, 14
	v_cmp_ge_u32_e64 s[6:7], v91, v74
	v_writelane_b32 v38, s40, 15
	v_writelane_b32 v39, s41, 15
	v_cmp_ge_u32_e64 s[8:9], v88, v74
	v_writelane_b32 v38, vcc_lo, 16
	v_writelane_b32 v39, vcc_hi, 16
	v_cmp_ge_u32_e64 s[40:41], v89, v74
	v_writelane_b32 v38, s6, 17
	v_writelane_b32 v39, s7, 17
	v_cmp_ge_u32_e32 vcc, v86, v74
	v_writelane_b32 v38, s8, 18
	v_writelane_b32 v39, s9, 18
	v_cmp_ge_u32_e64 s[6:7], v87, v74
	v_writelane_b32 v38, s40, 19
	v_writelane_b32 v39, s41, 19
	v_cmp_ge_u32_e64 s[8:9], v84, v74
	v_writelane_b32 v38, vcc_lo, 20
	v_writelane_b32 v39, vcc_hi, 20
	v_cmp_ge_u32_e64 s[40:41], v85, v74
	v_writelane_b32 v38, s6, 21
	v_writelane_b32 v39, s7, 21
	v_cmp_ge_u32_e32 vcc, v82, v74
	v_writelane_b32 v38, s8, 22
	v_writelane_b32 v39, s9, 22
	v_cmp_ge_u32_e64 s[6:7], v83, v74
	v_writelane_b32 v38, s40, 23
	v_writelane_b32 v39, s41, 23
	v_cmp_ge_u32_e64 s[8:9], v78, v74
	v_writelane_b32 v38, vcc_lo, 24
	v_writelane_b32 v39, vcc_hi, 24
	v_cmp_ge_u32_e64 s[40:41], v79, v74
	v_writelane_b32 v38, s6, 25
	v_writelane_b32 v39, s7, 25
	v_cmp_ge_u32_e32 vcc, v76, v74
	v_writelane_b32 v38, s8, 26
	v_writelane_b32 v39, s9, 26
	v_cmp_ge_u32_e64 s[6:7], v77, v74
	v_writelane_b32 v38, s40, 27
	v_writelane_b32 v39, s41, 27
	v_cmp_ge_u32_e64 s[8:9], v72, v74
	v_writelane_b32 v38, vcc_lo, 28
	v_writelane_b32 v39, vcc_hi, 28
	v_cmp_ge_u32_e64 s[40:41], v73, v74
	v_writelane_b32 v38, s6, 29
	v_writelane_b32 v39, s7, 29
	v_cmp_ge_u32_e32 vcc, v70, v74
	v_writelane_b32 v38, s8, 30
	v_writelane_b32 v39, s9, 30
	v_cmp_ge_u32_e64 s[6:7], v71, v74
	v_writelane_b32 v38, s40, 31
	v_writelane_b32 v39, s41, 31
	v_cmp_ge_u32_e64 s[8:9], v68, v74
	v_writelane_b32 v38, vcc_lo, 32
	v_writelane_b32 v39, vcc_hi, 32
	v_cmp_ge_u32_e64 s[40:41], v69, v74
	v_writelane_b32 v38, s6, 33
	v_writelane_b32 v39, s7, 33
	v_cmp_ge_u32_e32 vcc, v66, v74
	v_writelane_b32 v38, s8, 34
	v_writelane_b32 v39, s9, 34
	v_cmp_ge_u32_e64 s[6:7], v67, v74
	v_writelane_b32 v38, s40, 35
	v_writelane_b32 v39, s41, 35
	v_cmp_ge_u32_e64 s[8:9], v64, v74
	v_writelane_b32 v38, vcc_lo, 36
	v_writelane_b32 v39, vcc_hi, 36
	v_cmp_ge_u32_e64 s[40:41], v65, v74
	v_writelane_b32 v38, s6, 37
	v_writelane_b32 v39, s7, 37
	v_cmp_ge_u32_e32 vcc, v62, v74
	v_writelane_b32 v38, s8, 38
	v_writelane_b32 v39, s9, 38
	v_cmp_ge_u32_e64 s[6:7], v63, v74
	v_writelane_b32 v38, s40, 39
	v_writelane_b32 v39, s41, 39
	v_cmp_ge_u32_e64 s[8:9], v60, v74
	v_writelane_b32 v38, vcc_lo, 40
	v_writelane_b32 v39, vcc_hi, 40
	v_cmp_ge_u32_e64 s[40:41], v61, v74
	v_writelane_b32 v38, s6, 41
	v_writelane_b32 v39, s7, 41
	v_cmp_ge_u32_e32 vcc, v56, v74
	v_writelane_b32 v38, s8, 42
	v_writelane_b32 v39, s9, 42
	v_cmp_ge_u32_e64 s[6:7], v57, v74
	v_writelane_b32 v38, s40, 43
	v_writelane_b32 v39, s41, 43
	v_cmp_ge_u32_e64 s[8:9], v54, v74
	v_writelane_b32 v38, vcc_lo, 44
	v_writelane_b32 v39, vcc_hi, 44
	v_cmp_ge_u32_e64 s[40:41], v55, v74
	v_writelane_b32 v38, s6, 45
	v_writelane_b32 v39, s7, 45
	v_cmp_ge_u32_e32 vcc, v52, v74
	v_writelane_b32 v38, s8, 46
	v_writelane_b32 v39, s9, 46
	v_cmp_ge_u32_e64 s[6:7], v53, v74
	v_writelane_b32 v38, s40, 47
; #define TK_WL2(dlo, dhi, vlo, vhi, ln) asm volatile("s_nop 4\n\tv_writelane_b32 %0, %2, %4\n\tv_writelane_b32 %1, %3, %4" : "+v"(dlo), "+v"(dhi) : "s"(vlo), "s"(vhi), "n"(ln))
; template <int NCH>
; __device__ __forceinline__ void dsa_topk_query(unsigned char* ws, const float* srow  , LAS unsigned* hist  , int t, int lane_in) {
;     ...
;     if (ge) {
;         int a_lo = 0, a_hi = 0, b_lo = 0, b_hi = 0;
;     ...
; #pragma unroll
;         for (int c = 0; c < NCH; ++c) { const u64 sm = __ballot(u[c] >= T); const int slo = (int)(unsigned)sm, shi = (int)(unsigned)(sm >> 32);
;             if (c < 64) TK_WL2(a_lo, a_hi, slo, shi, c & 63); else TK_WL2(b_lo, b_hi, slo, shi, c & 63); }
;     ...
;         bm[lane] = ((u64)(unsigned)a_hi << 32) | (unsigned)a_lo; bm[64 + lane] = ((u64)(unsigned)b_hi << 32) | (unsigned)b_lo;
;         return;
	v_writelane_b32 v39, s41, 47
	v_cmp_ge_u32_e64 s[8:9], v50, v74
	v_writelane_b32 v38, vcc_lo, 48
	v_writelane_b32 v39, vcc_hi, 48
	v_cmp_ge_u32_e64 s[40:41], v51, v74
	v_writelane_b32 v38, s6, 49
	v_writelane_b32 v39, s7, 49
	v_cmp_ge_u32_e32 vcc, v48, v74
	v_writelane_b32 v38, s8, 50
	v_writelane_b32 v39, s9, 50
	v_cmp_ge_u32_e64 s[6:7], v49, v74
	v_writelane_b32 v38, s40, 51
	v_writelane_b32 v39, s41, 51
	v_cmp_ge_u32_e64 s[8:9], v46, v74
	v_writelane_b32 v38, vcc_lo, 52
	v_writelane_b32 v39, vcc_hi, 52
	v_cmp_ge_u32_e64 s[40:41], v47, v74
	v_writelane_b32 v38, s6, 53
	v_writelane_b32 v39, s7, 53
	v_cmp_ge_u32_e32 vcc, v44, v74
	v_writelane_b32 v38, s8, 54
	v_writelane_b32 v39, s9, 54
	v_cmp_ge_u32_e64 s[6:7], v45, v74
	v_writelane_b32 v38, s40, 55
	v_writelane_b32 v39, s41, 55
	v_cmp_ge_u32_e64 s[8:9], v40, v74
	v_writelane_b32 v38, vcc_lo, 56
	v_writelane_b32 v39, vcc_hi, 56
	v_cmp_ge_u32_e64 s[40:41], v41, v74
	v_writelane_b32 v38, s6, 57
	v_writelane_b32 v39, s7, 57
	v_cmp_ge_u32_e32 vcc, v36, v74
	v_writelane_b32 v38, s8, 58
	v_writelane_b32 v39, s9, 58
	v_cmp_ge_u32_e64 s[6:7], v37, v74
	v_writelane_b32 v38, s40, 59
	v_writelane_b32 v39, s41, 59
	v_cmp_ge_u32_e64 s[8:9], v2, v74
	v_writelane_b32 v38, vcc_lo, 60
	v_writelane_b32 v39, vcc_hi, 60
	v_cmp_ge_u32_e64 s[40:41], v1, v74
	v_writelane_b32 v38, s6, 61
	v_writelane_b32 v39, s7, 61
	v_cmp_ge_u32_e32 vcc, v32, v74
	v_mov_b32_e32 v36, 0
	v_mov_b32_e32 v37, 0
	v_writelane_b32 v38, s8, 62
	v_writelane_b32 v39, s9, 62
	v_cmp_ge_u32_e64 s[6:7], v33, v74
	v_writelane_b32 v38, s40, 63
	v_writelane_b32 v39, s41, 63
	v_cmp_ge_u32_e64 s[8:9], v34, v74
	v_writelane_b32 v36, vcc_lo, 0
	v_writelane_b32 v37, vcc_hi, 0
	v_cmp_ge_u32_e64 s[40:41], v35, v74
	v_writelane_b32 v36, s6, 1
	v_writelane_b32 v37, s7, 1
	v_cmp_ge_u32_e32 vcc, v28, v74
	v_writelane_b32 v36, s8, 2
	v_writelane_b32 v37, s9, 2
	v_cmp_ge_u32_e64 s[6:7], v29, v74
	v_writelane_b32 v36, s40, 3
	v_writelane_b32 v37, s41, 3
	v_cmp_ge_u32_e64 s[8:9], v30, v74
	v_writelane_b32 v36, vcc_lo, 4
	v_writelane_b32 v37, vcc_hi, 4
	v_cmp_ge_u32_e64 s[40:41], v31, v74
	v_writelane_b32 v36, s6, 5
	v_writelane_b32 v37, s7, 5
	v_cmp_ge_u32_e32 vcc, v24, v74
	v_writelane_b32 v36, s8, 6
	v_writelane_b32 v37, s9, 6
	v_cmp_ge_u32_e64 s[6:7], v25, v74
	v_writelane_b32 v36, s40, 7
	v_writelane_b32 v37, s41, 7
	v_cmp_ge_u32_e64 s[8:9], v26, v74
	v_writelane_b32 v36, vcc_lo, 8
	v_writelane_b32 v37, vcc_hi, 8
	v_cmp_ge_u32_e64 s[40:41], v27, v74
	v_writelane_b32 v36, s6, 9
	v_writelane_b32 v37, s7, 9
	v_cmp_ge_u32_e32 vcc, v20, v74
	v_writelane_b32 v36, s8, 10
	v_writelane_b32 v37, s9, 10
	v_cmp_ge_u32_e64 s[6:7], v21, v74
	v_writelane_b32 v36, s40, 11
	v_writelane_b32 v37, s41, 11
	v_cmp_ge_u32_e64 s[8:9], v22, v74
	v_writelane_b32 v36, vcc_lo, 12
	v_writelane_b32 v37, vcc_hi, 12
	v_cmp_ge_u32_e64 s[40:41], v23, v74
	v_writelane_b32 v36, s6, 13
	v_writelane_b32 v37, s7, 13
	v_cmp_ge_u32_e32 vcc, v16, v74
	v_writelane_b32 v36, s8, 14
	v_writelane_b32 v37, s9, 14
	v_cmp_ge_u32_e64 s[6:7], v17, v74
	v_writelane_b32 v36, s40, 15
	v_writelane_b32 v37, s41, 15
	v_cmp_ge_u32_e64 s[8:9], v18, v74
	v_writelane_b32 v36, vcc_lo, 16
	v_writelane_b32 v37, vcc_hi, 16
	v_cmp_ge_u32_e64 s[40:41], v19, v74
	v_writelane_b32 v36, s6, 17
	v_writelane_b32 v37, s7, 17
	v_cmp_ge_u32_e32 vcc, v12, v74
	v_writelane_b32 v36, s8, 18
	v_writelane_b32 v37, s9, 18
	v_cmp_ge_u32_e64 s[6:7], v13, v74
	v_writelane_b32 v36, s40, 19
	v_writelane_b32 v37, s41, 19
	v_cmp_ge_u32_e64 s[8:9], v14, v74
	v_writelane_b32 v36, vcc_lo, 20
	v_writelane_b32 v37, vcc_hi, 20
	v_cmp_ge_u32_e64 s[40:41], v15, v74
	v_writelane_b32 v36, s6, 21
	v_writelane_b32 v37, s7, 21
	v_cmp_ge_u32_e32 vcc, v8, v74
	v_writelane_b32 v36, s8, 22
	v_writelane_b32 v37, s9, 22
	v_cmp_ge_u32_e64 s[6:7], v9, v74
	v_writelane_b32 v36, s40, 23
	v_writelane_b32 v37, s41, 23
	v_cmp_ge_u32_e64 s[8:9], v10, v74
	v_writelane_b32 v36, vcc_lo, 24
	v_writelane_b32 v37, vcc_hi, 24
	v_cmp_ge_u32_e64 s[40:41], v11, v74
	v_writelane_b32 v36, s6, 25
	v_writelane_b32 v37, s7, 25
	v_cmp_ge_u32_e32 vcc, v4, v74
	v_writelane_b32 v36, s8, 26
	v_writelane_b32 v37, s9, 26
	v_cmp_ge_u32_e64 s[6:7], v5, v74
	v_writelane_b32 v36, s40, 27
	v_writelane_b32 v37, s41, 27
	v_cmp_ge_u32_e64 s[8:9], v6, v74
	v_writelane_b32 v36, vcc_lo, 28
	v_writelane_b32 v37, vcc_hi, 28
	v_cmp_ge_u32_e64 s[40:41], v7, v74
	v_lshl_add_u64 v[4:5], v[80:81], 3, s[60:61]
	v_writelane_b32 v36, s6, 29
	v_writelane_b32 v37, s7, 29
	v_writelane_b32 v36, s8, 30
	v_writelane_b32 v37, s9, 30
	v_writelane_b32 v36, s40, 31
	v_writelane_b32 v37, s41, 31
	global_store_dwordx2 v[4:5], v[38:39], off
	global_store_dwordx2 v[4:5], v[36:37], off offset:512
	s_mov_b64 s[0:1], 0

; #define TK_WL2(dlo, dhi, vlo, vhi, ln) asm volatile("s_nop 4\n\tv_writelane_b32 %0, %2, %4\n\tv_writelane_b32 %1, %3, %4" : "+v"(dlo), "+v"(dhi) : "s"(vlo), "s"(vhi), "n"(ln))
; template <int NCH>
; __device__ __forceinline__ void dsa_topk_query(unsigned char* ws, const float* srow  , LAS unsigned* hist  , int t, int lane_in) {
;     ...
;     if (ge) {
;         int a_lo = 0, a_hi = 0, b_lo = 0, b_hi = 0;
;     ...
; #pragma unroll
;         for (int c = 0; c < NCH; ++c) { const u64 sm = __ballot(u[c] >= T); const int slo = (int)(unsigned)sm, shi = (int)(unsigned)(sm >> 32);
;             if (c < 64) TK_WL2(a_lo, a_hi, slo, shi, c & 63); else TK_WL2(b_lo, b_hi, slo, shi, c & 63); }
;     ...
;         bm[lane] = ((u64)(unsigned)a_hi << 32) | (unsigned)a_lo; bm[64 + lane] = ((u64)(unsigned)b_hi << 32) | (unsigned)b_lo;
;         return;
.LBB0_4490:
	s_and_b64 vcc, exec, s[0:1]
	s_cbranch_vccz .LBB0_4492
	v_cmp_ge_u32_e32 vcc, v2, v74
	v_mov_b32_e32 v68, 0
	v_mov_b32_e32 v69, 0
	v_cmp_ge_u32_e64 s[6:7], v1, v74
	v_cmp_ge_u32_e64 s[8:9], v62, v74
	s_nop 1
	v_writelane_b32 v68, vcc_lo, 0
	v_writelane_b32 v69, vcc_hi, 0
	v_cmp_ge_u32_e64 s[40:41], v63, v74
	v_writelane_b32 v68, s6, 1
	v_writelane_b32 v69, s7, 1
	v_cmp_ge_u32_e32 vcc, v64, v74
	v_writelane_b32 v68, s8, 2
	v_writelane_b32 v69, s9, 2
	v_cmp_ge_u32_e64 s[6:7], v65, v74
	v_writelane_b32 v68, s40, 3
	v_writelane_b32 v69, s41, 3
	v_cmp_ge_u32_e64 s[8:9], v66, v74
	v_writelane_b32 v68, vcc_lo, 4
	v_writelane_b32 v69, vcc_hi, 4
	v_cmp_ge_u32_e64 s[40:41], v67, v74
	v_writelane_b32 v68, s6, 5
	v_writelane_b32 v69, s7, 5
	v_cmp_ge_u32_e32 vcc, v56, v74
	v_writelane_b32 v68, s8, 6
	v_writelane_b32 v69, s9, 6
	v_cmp_ge_u32_e64 s[6:7], v57, v74
	v_writelane_b32 v68, s40, 7
	v_writelane_b32 v69, s41, 7
	v_cmp_ge_u32_e64 s[8:9], v58, v74
	v_writelane_b32 v68, vcc_lo, 8
	v_writelane_b32 v69, vcc_hi, 8
	v_cmp_ge_u32_e64 s[40:41], v59, v74
	v_writelane_b32 v68, s6, 9
	v_writelane_b32 v69, s7, 9
	v_cmp_ge_u32_e32 vcc, v52, v74
	v_writelane_b32 v68, s8, 10
	v_writelane_b32 v69, s9, 10
	v_cmp_ge_u32_e64 s[6:7], v53, v74
	v_writelane_b32 v68, s40, 11
	v_writelane_b32 v69, s41, 11
	v_cmp_ge_u32_e64 s[8:9], v54, v74
	v_writelane_b32 v68, vcc_lo, 12
	v_writelane_b32 v69, vcc_hi, 12
	v_cmp_ge_u32_e64 s[40:41], v55, v74
	v_writelane_b32 v68, s6, 13
	v_writelane_b32 v69, s7, 13
	v_cmp_ge_u32_e32 vcc, v48, v74
	v_writelane_b32 v68, s8, 14
	v_writelane_b32 v69, s9, 14
	v_cmp_ge_u32_e64 s[6:7], v49, v74
	v_writelane_b32 v68, s40, 15
	v_writelane_b32 v69, s41, 15
	v_cmp_ge_u32_e64 s[8:9], v50, v74
	v_writelane_b32 v68, vcc_lo, 16
	v_writelane_b32 v69, vcc_hi, 16
	v_cmp_ge_u32_e64 s[40:41], v51, v74
	v_writelane_b32 v68, s6, 17
	v_writelane_b32 v69, s7, 17
	v_cmp_ge_u32_e32 vcc, v44, v74
	v_writelane_b32 v68, s8, 18
	v_writelane_b32 v69, s9, 18
	v_cmp_ge_u32_e64 s[6:7], v45, v74
	v_writelane_b32 v68, s40, 19
	v_writelane_b32 v69, s41, 19
	v_cmp_ge_u32_e64 s[8:9], v46, v74
	v_writelane_b32 v68, vcc_lo, 20
	v_writelane_b32 v69, vcc_hi, 20
	v_cmp_ge_u32_e64 s[40:41], v47, v74
	v_writelane_b32 v68, s6, 21
	v_writelane_b32 v69, s7, 21
	v_cmp_ge_u32_e32 vcc, v40, v74
	v_writelane_b32 v68, s8, 22
	v_writelane_b32 v69, s9, 22
	v_cmp_ge_u32_e64 s[6:7], v41, v74
	v_writelane_b32 v68, s40, 23
	v_writelane_b32 v69, s41, 23
	v_cmp_ge_u32_e64 s[8:9], v42, v74
	v_writelane_b32 v68, vcc_lo, 24
	v_writelane_b32 v69, vcc_hi, 24
	v_cmp_ge_u32_e64 s[40:41], v43, v74
	v_writelane_b32 v68, s6, 25
	v_writelane_b32 v69, s7, 25
	v_cmp_ge_u32_e32 vcc, v36, v74
	v_writelane_b32 v68, s8, 26
	v_writelane_b32 v69, s9, 26
	v_cmp_ge_u32_e64 s[6:7], v37, v74
	v_writelane_b32 v68, s40, 27
	v_writelane_b32 v69, s41, 27
	v_cmp_ge_u32_e64 s[8:9], v38, v74
	v_writelane_b32 v68, vcc_lo, 28
	v_writelane_b32 v69, vcc_hi, 28
	v_cmp_ge_u32_e64 s[40:41], v39, v74
	v_writelane_b32 v68, s6, 29
	v_writelane_b32 v69, s7, 29
	v_cmp_ge_u32_e32 vcc, v32, v74
	v_writelane_b32 v68, s8, 30
	v_writelane_b32 v69, s9, 30
	v_cmp_ge_u32_e64 s[6:7], v33, v74
	v_writelane_b32 v68, s40, 31
	v_writelane_b32 v69, s41, 31
	v_cmp_ge_u32_e64 s[8:9], v34, v74
	v_writelane_b32 v68, vcc_lo, 32
	v_writelane_b32 v69, vcc_hi, 32
	v_cmp_ge_u32_e64 s[40:41], v35, v74
	v_writelane_b32 v68, s6, 33
	v_writelane_b32 v69, s7, 33
	v_cmp_ge_u32_e32 vcc, v28, v74
	v_writelane_b32 v68, s8, 34
	v_writelane_b32 v69, s9, 34
	v_cmp_ge_u32_e64 s[6:7], v29, v74
	v_writelane_b32 v68, s40, 35
	v_writelane_b32 v69, s41, 35
	v_cmp_ge_u32_e64 s[8:9], v30, v74
	v_writelane_b32 v68, vcc_lo, 36
	v_writelane_b32 v69, vcc_hi, 36
	v_cmp_ge_u32_e64 s[40:41], v31, v74
	v_writelane_b32 v68, s6, 37
	v_writelane_b32 v69, s7, 37
	v_cmp_ge_u32_e32 vcc, v24, v74
	v_writelane_b32 v68, s8, 38
	v_writelane_b32 v69, s9, 38
	v_cmp_ge_u32_e64 s[6:7], v25, v74
	v_writelane_b32 v68, s40, 39
	v_writelane_b32 v69, s41, 39
	v_cmp_ge_u32_e64 s[8:9], v26, v74
	v_writelane_b32 v68, vcc_lo, 40
	v_writelane_b32 v69, vcc_hi, 40
	v_cmp_ge_u32_e64 s[40:41], v27, v74
	v_writelane_b32 v68, s6, 41
	v_writelane_b32 v69, s7, 41
	v_cmp_ge_u32_e32 vcc, v16, v74
	v_writelane_b32 v68, s8, 42
	v_writelane_b32 v69, s9, 42
	v_cmp_ge_u32_e64 s[6:7], v17, v74
	v_writelane_b32 v68, s40, 43
	v_writelane_b32 v69, s41, 43
	v_cmp_ge_u32_e64 s[8:9], v18, v74
	v_writelane_b32 v68, vcc_lo, 44
	v_writelane_b32 v69, vcc_hi, 44
	v_cmp_ge_u32_e64 s[40:41], v19, v74
	v_writelane_b32 v68, s6, 45
	v_writelane_b32 v69, s7, 45
	v_cmp_ge_u32_e32 vcc, v20, v74
	v_writelane_b32 v68, s8, 46
	v_writelane_b32 v69, s9, 46
	v_cmp_ge_u32_e64 s[6:7], v21, v74
	v_writelane_b32 v68, s40, 47
	v_writelane_b32 v69, s41, 47
	v_cmp_ge_u32_e64 s[8:9], v22, v74
	v_writelane_b32 v68, vcc_lo, 48
	v_writelane_b32 v69, vcc_hi, 48
	v_cmp_ge_u32_e64 s[40:41], v23, v74
	v_writelane_b32 v68, s6, 49
	v_writelane_b32 v69, s7, 49
	v_cmp_ge_u32_e32 vcc, v12, v74
	v_writelane_b32 v68, s8, 50
	v_writelane_b32 v69, s9, 50
	v_cmp_ge_u32_e64 s[6:7], v13, v74
	v_writelane_b32 v68, s40, 51
	v_writelane_b32 v69, s41, 51
	v_cmp_ge_u32_e64 s[8:9], v14, v74
	v_writelane_b32 v68, vcc_lo, 52
	v_writelane_b32 v69, vcc_hi, 52
	v_cmp_ge_u32_e64 s[40:41], v15, v74
	v_writelane_b32 v68, s6, 53
	v_writelane_b32 v69, s7, 53
	v_cmp_ge_u32_e32 vcc, v8, v74
	v_writelane_b32 v68, s8, 54
	v_writelane_b32 v69, s9, 54
	v_cmp_ge_u32_e64 s[6:7], v9, v74
	v_writelane_b32 v68, s40, 55
	v_writelane_b32 v69, s41, 55
	v_cmp_ge_u32_e64 s[8:9], v10, v74
	v_writelane_b32 v68, vcc_lo, 56
	v_writelane_b32 v69, vcc_hi, 56
	v_cmp_ge_u32_e64 s[40:41], v11, v74
	v_writelane_b32 v68, s6, 57
	v_writelane_b32 v69, s7, 57
	v_cmp_ge_u32_e32 vcc, v4, v74
	v_writelane_b32 v68, s8, 58
	v_writelane_b32 v69, s9, 58
	v_cmp_ge_u32_e64 s[6:7], v5, v74
	v_writelane_b32 v68, s40, 59
	v_writelane_b32 v69, s41, 59
	v_cmp_ge_u32_e64 s[8:9], v6, v74
	v_writelane_b32 v68, vcc_lo, 60
	v_writelane_b32 v69, vcc_hi, 60
	v_cmp_ge_u32_e64 s[40:41], v7, v74
	v_lshl_add_u64 v[4:5], v[60:61], 3, s[60:61]
	v_writelane_b32 v68, s6, 61
	v_writelane_b32 v69, s7, 61
	v_writelane_b32 v68, s8, 62
	v_writelane_b32 v69, s9, 62
	v_writelane_b32 v68, s40, 63
	v_writelane_b32 v69, s41, 63
	global_store_dwordx2 v[4:5], v[68:69], off
	global_store_dwordx2 v[4:5], v[238:239], off offset:512
